# GEMM prologues: K-tile 1 staging issued before the first wait (all 8 GEMM phases)
# speedup vs baseline: 1.0070x; 1.0018x over previous
; #define PG8_STAGE(bufoff, gbase, voff) do { _Pragma("unroll") for (int _i = 0; _i < 2; ++_i) \
;         __builtin_amdgcn_global_load_lds((const unsigned*)((const char*)(gbase) + (voff)[_i]), (PG8_LAS unsigned*)(lds + (bufoff) + ldsw + _i * 8192), 16, 0, 0); } while (0)
; #define PG8_WAIT_V(n) asm volatile("s_waitcnt vmcnt(" #n ")" ::: "memory")
; #define PG8_BAR __builtin_amdgcn_s_barrier()
; template <class Epi, class Sched, bool ALIGN_EPI = false, bool SP2 = false>
; __device__ __forceinline__ void gemm_phase(PG8_LAS unsigned char* lds, const Gemm g, const Sched& S, const Epi& E, int wv) {
;     ...
;     const unsigned ldsw = (unsigned)wid * 1024u;
;     const int aoff = lds_byte(wr * 64 + fr, fq * 8), boff = lds_byte(wc * 32 + fr, fq * 8);
;     ...
;         PG8_STAGE(PG8_SB(0, 0), cB, voffB); PG8_STAGE(PG8_SB(0, 1), cB + hstepB, voffB); PG8_STAGE(PG8_SA(0, 0), cA, voffA); PG8_STAGE(PG8_SA(0, 1), cA + hstepA, voffA);
;         if (wr == 1) PG8_BAR;
;         PG8_WAIT_V(2); PG8_BAR;
;         PG8_STAGE(PG8_SB(1, 0), cB + kstep, voffB); PG8_STAGE(PG8_SA(1, 0), cA + kstep, voffA); PG8_STAGE(PG8_SB(1, 1), cB + hstepB + kstep, voffB);
;         PG8_WAIT_V(6); PG8_BAR;
.LBB0_243:
	s_ashr_i32 s71, s5, 3
	s_add_u32 s16, s78, 0x5300000
	s_addc_u32 s17, s79, 0
	s_add_u32 s18, s78, 0x9300000
	s_addc_u32 s19, s79, 0
	s_add_u32 s20, s78, 0xd300000
	s_addc_u32 s21, s79, 0
	s_add_u32 s22, s78, 0x11300000
	s_addc_u32 s23, s79, 0
	s_add_u32 s24, s78, 0x1eb00000
	s_mov_b64 s[26:27], 0x80
	s_addc_u32 s25, s79, 0
	s_and_b32 s7, s4, 3
	s_add_i32 m0, s59, 0x18000
	v_lshl_add_u64 v[6:7], v[6:7], 0, s[26:27]
	s_ashr_i32 s64, s89, 31
	s_lshl_b32 s28, s3, 13
	s_lshl_b32 s29, s7, 12
	global_load_lds_dwordx4 v[6:7], off
	v_lshl_add_u64 v[4:5], v[4:5], 0, s[26:27]
	s_add_i32 m0, s59, 0x1a000
	s_add_i32 s65, s59, 0x8000
	s_add_i32 s66, s59, 0xa000
	global_load_lds_dwordx4 v[4:5], off
	v_lshl_add_u64 v[0:1], v[0:1], 0, s[26:27]
	s_mov_b32 m0, s65
	s_add_u32 s4, s50, 0x80080
	global_load_lds_dwordx4 v[0:1], off
	v_lshl_add_u64 v[0:1], v[2:3], 0, s[26:27]
	s_mov_b32 m0, s66
	s_addc_u32 s5, s51, 0
	global_load_lds_dwordx4 v[0:1], off
	s_add_i32 m0, s59, 0x1c000
	v_lshl_add_u64 v[0:1], s[4:5], 0, v[140:141]
	global_load_lds_dwordx4 v[0:1], off
	v_lshl_add_u64 v[0:1], s[4:5], 0, v[136:137]
	s_add_i32 m0, s59, 0x1e000
	s_cmpk_lt_u32 s2, 0x100
	global_load_lds_dwordx4 v[0:1], off
	s_waitcnt vmcnt(8)
	s_barrier
	v_bfe_u32 v1, v8, 4, 2
	v_and_b32_e32 v0, 15, v8
	v_lshlrev_b32_e32 v3, 4, v1
	v_lshl_or_b32 v147, s3, 6, v0
	v_lshl_or_b32 v0, v0, 6, v3
	v_lshlrev_b32_e32 v3, 2, v8
	v_and_b32_e32 v3, 32, v3
	v_lshlrev_b32_e32 v2, 3, v1
	v_bitop3_b32 v4, v0, s28, v3 bitop3:0xde
	v_bitop3_b32 v172, v0, s29, v3 bitop3:0xde
	v_lshlrev_b32_e32 v0, 2, v1
	v_lshl_or_b32 v146, s7, 5, v2
	v_lshl_or_b32 v2, s7, 4, v0
	v_lshlrev_b32_e32 v144, 2, v2
	v_cmp_eq_u32_e64 s[2:3], 0, v1
	v_lshl_add_u64 v[0:1], s[78:79], 0, v[144:145]
	s_mov_b64 s[4:5], 0x400000
	v_lshl_add_u64 v[148:149], v[0:1], 0, s[4:5]
	s_mov_b64 s[4:5], 0x600000
	v_lshlrev_b32_e32 v144, 1, v2
	v_lshl_add_u64 v[150:151], v[0:1], 0, s[4:5]
	v_lshl_add_u64 v[0:1], s[78:79], 0, v[144:145]
	s_mov_b64 s[4:5], 0x800000
	v_lshl_add_u64 v[152:153], v[0:1], 0, s[4:5]
	v_lshlrev_b32_e32 v0, 15, v13
	v_and_b32_e32 v0, 0xffff0000, v0
	v_lshl_add_u32 v0, v12, 12, v0
	v_and_b32_e32 v1, 1, v13
	v_lshl_or_b32 v0, v1, 6, v0
	v_lshl_add_u32 v154, v14, 1, v0
	v_lshlrev_b32_e32 v0, 15, v9
	v_and_b32_e32 v0, 0xffff0000, v0
	v_lshl_add_u32 v0, v10, 12, v0
	v_and_b32_e32 v1, 1, v9
	s_waitcnt vmcnt(6)
	s_cselect_b64 s[28:29], -1, 0
	s_cmp_lt_u32 s7, 2
	v_lshl_or_b32 v0, v1, 6, v0
	s_cselect_b64 s[30:31], -1, 0
	v_lshl_add_u32 v156, v11, 1, v0
	s_add_i32 s67, 0, 0x10000
	s_add_i32 s68, 0, 0x14000
	v_mbcnt_lo_u32_b32 v0, -1, 0
	v_mov_b32_e32 v155, v145
	v_mov_b32_e32 v157, v145
	v_mov_b64_e32 v[158:159], 0x900
	v_mov_b64_e32 v[160:161], 0x8ff
	v_add_u32_e32 v173, s67, v172
	v_add_u32_e32 v174, s68, v172
	v_add_u32_e32 v175, 0, v4
	s_mov_b64 s[34:35], 0x4000
	s_mov_b64 s[36:37], 0x4800
	s_mov_b64 s[38:39], 0x5000
	s_mov_b64 s[40:41], 0x5800
	s_mov_b32 s69, 0x1d300000
	s_mov_b32 s70, 0x1eb20000
	v_mbcnt_hi_u32_b32 v176, -1, v0
	s_barrier
	s_branch .LBB0_246

; #define PG8_STAGE(bufoff, gbase, voff) do { _Pragma("unroll") for (int _i = 0; _i < 2; ++_i) \
;         __builtin_amdgcn_global_load_lds((const unsigned*)((const char*)(gbase) + (voff)[_i]), (PG8_LAS unsigned*)(lds + (bufoff) + ldsw + _i * 8192), 16, 0, 0); } while (0)
; #define PG8_WAIT_V(n) asm volatile("s_waitcnt vmcnt(" #n ")" ::: "memory")
; #define PG8_BAR __builtin_amdgcn_s_barrier()
; template <class Epi, class Sched, bool ALIGN_EPI = false, bool SP2 = false>
; __device__ __forceinline__ void gemm_phase(PG8_LAS unsigned char* lds, const Gemm g, const Sched& S, const Epi& E, int wv) {
;     ...
;     const unsigned ldsw = (unsigned)wid * 1024u;
;     const int aoff = lds_byte(wr * 64 + fr, fq * 8), boff = lds_byte(wc * 32 + fr, fq * 8);
;     ...
;         PG8_STAGE(PG8_SB(0, 0), cB, voffB); PG8_STAGE(PG8_SB(0, 1), cB + hstepB, voffB); PG8_STAGE(PG8_SA(0, 0), cA, voffA); PG8_STAGE(PG8_SA(0, 1), cA + hstepA, voffA);
;         if (wr == 1) PG8_BAR;
;         PG8_WAIT_V(2); PG8_BAR;
;         PG8_STAGE(PG8_SB(1, 0), cB + kstep, voffB); PG8_STAGE(PG8_SA(1, 0), cA + kstep, voffA); PG8_STAGE(PG8_SB(1, 1), cB + hstepB + kstep, voffB);
;         PG8_WAIT_V(6); PG8_BAR;
.LBB0_471:
	s_add_u32 s10, s78, 0x1eb20000
	s_addc_u32 s11, s79, 0
	s_lshl_b32 s5, s12, 5
	s_mov_b64 s[12:13], 0x80
	s_and_b32 s18, s5, 0x60
	s_add_i32 m0, s40, 0x18000
	v_lshl_add_u64 v[6:7], v[6:7], 0, s[12:13]
	s_lshl_b32 s15, s14, 13
	s_lshl_b32 s19, s18, 7
	global_load_lds_dwordx4 v[6:7], off
	v_lshl_add_u64 v[4:5], v[4:5], 0, s[12:13]
	s_add_i32 m0, s40, 0x1a000
	s_add_i32 s45, s40, 0x8000
	s_add_i32 s46, s40, 0xa000
	global_load_lds_dwordx4 v[4:5], off
	v_lshl_add_u64 v[0:1], v[0:1], 0, s[12:13]
	s_mov_b32 m0, s45
	s_add_u32 s16, s24, 0x20080
	global_load_lds_dwordx4 v[0:1], off
	v_lshl_add_u64 v[0:1], v[2:3], 0, s[12:13]
	s_mov_b32 m0, s46
	s_addc_u32 s17, s25, 0
	global_load_lds_dwordx4 v[0:1], off
	s_add_i32 m0, s40, 0x1c000
	v_lshl_add_u64 v[0:1], s[16:17], 0, v[132:133]
	global_load_lds_dwordx4 v[0:1], off
	v_lshl_add_u64 v[0:1], s[16:17], 0, v[128:129]
	s_add_i32 m0, s40, 0x1e000
	s_cmpk_lt_u32 s3, 0x100
	global_load_lds_dwordx4 v[0:1], off
	s_waitcnt vmcnt(8)
	s_barrier
	v_lshrrev_b32_e32 v1, 1, v8
	v_and_b32_e32 v1, 24, v1
	v_and_b32_e32 v0, 15, v8
	v_lshlrev_b32_e32 v2, 1, v1
	v_lshl_or_b32 v152, s14, 6, v0
	v_lshl_or_b32 v0, v0, 6, v2
	v_lshlrev_b32_e32 v2, 2, v8
	v_and_b32_e32 v2, 32, v2
	v_bitop3_b32 v3, v0, s15, v2 bitop3:0xde
	v_bitop3_b32 v153, v0, s19, v2 bitop3:0xde
	v_lshlrev_b32_e32 v0, 13, v12
	v_and_b32_e32 v0, 0xffffc000, v0
	v_or_b32_e32 v154, s18, v1
	v_lshl_add_u32 v0, v13, 10, v0
	v_and_b32_e32 v1, 1, v12
	v_lshl_or_b32 v0, v1, 6, v0
	v_lshl_add_u32 v136, v14, 1, v0
	v_lshlrev_b32_e32 v0, 13, v9
	v_and_b32_e32 v0, 0xffffc000, v0
	s_waitcnt vmcnt(6)
	v_lshl_add_u32 v0, v10, 10, v0
	v_and_b32_e32 v1, 1, v9
	s_cselect_b64 s[14:15], -1, 0
	v_lshl_or_b32 v0, v1, 6, v0
	s_add_i32 s47, 0, 0x10000
	s_add_i32 s48, 0, 0x14000
	s_sext_i32_i8 s5, s2
	v_mov_b32_e32 v137, v133
	v_lshl_add_u32 v138, v11, 1, v0
	v_mov_b32_e32 v139, v133
	v_mov_b64_e32 v[140:141], 0x300
	v_mov_b64_e32 v[142:143], 0x2ff
	v_add_u32_e32 v155, s47, v153
	v_add_u32_e32 v156, s48, v153
	v_add_u32_e32 v157, 0, v3
	s_movk_i32 s49, 0x1800
	v_mov_b32_e32 v158, 0x358637bd
	s_mov_b32 s51, 0xf800000
	v_mov_b32_e32 v159, 0x260
	s_barrier
	s_branch .LBB0_474

; #define PG8_STAGE(bufoff, gbase, voff) do { _Pragma("unroll") for (int _i = 0; _i < 2; ++_i) \
;         __builtin_amdgcn_global_load_lds((const unsigned*)((const char*)(gbase) + (voff)[_i]), (PG8_LAS unsigned*)(lds + (bufoff) + ldsw + _i * 8192), 16, 0, 0); } while (0)
; #define PG8_WAIT_V(n) asm volatile("s_waitcnt vmcnt(" #n ")" ::: "memory")
; #define PG8_BAR __builtin_amdgcn_s_barrier()
; template <class Epi, class Sched, bool ALIGN_EPI = false, bool SP2 = false>
; __device__ __forceinline__ void gemm_phase(PG8_LAS unsigned char* lds, const Gemm g, const Sched& S, const Epi& E, int wv) {
;     ...
;     const unsigned ldsw = (unsigned)wid * 1024u;
;     const int aoff = lds_byte(wr * 64 + fr, fq * 8), boff = lds_byte(wc * 32 + fr, fq * 8);
;     ...
;         PG8_STAGE(PG8_SB(0, 0), cB, voffB); PG8_STAGE(PG8_SB(0, 1), cB + hstepB, voffB); PG8_STAGE(PG8_SA(0, 0), cA, voffA); PG8_STAGE(PG8_SA(0, 1), cA + hstepA, voffA);
;         if (wr == 1) PG8_BAR;
;         PG8_WAIT_V(2); PG8_BAR;
;         PG8_STAGE(PG8_SB(1, 0), cB + kstep, voffB); PG8_STAGE(PG8_SA(1, 0), cA + kstep, voffA); PG8_STAGE(PG8_SB(1, 1), cB + hstepB + kstep, voffB);
;         PG8_WAIT_V(6); PG8_BAR;
.LBB0_487:
	s_lshl_b32 s5, s8, 5
	s_and_b32 s20, s5, 0x60
	s_lshl_b32 s17, s16, 13
	s_lshl_b32 s21, s20, 7
	s_add_u32 s8, s78, 0x15300000
	s_addc_u32 s9, s79, 0
	s_add_u32 s10, s78, 0x19300000
	s_addc_u32 s11, s79, 0
	s_add_u32 s12, s78, 0x1eb30000
	s_mov_b64 s[14:15], 0x80
	s_addc_u32 s13, s79, 0
	s_add_i32 m0, s56, 0x18000
	v_lshl_add_u64 v[6:7], v[6:7], 0, s[14:15]
	global_load_lds_dwordx4 v[6:7], off
	v_lshl_add_u64 v[4:5], v[4:5], 0, s[14:15]
	s_add_i32 m0, s56, 0x1a000
	s_add_i32 s60, s56, 0x8000
	s_add_i32 s61, s56, 0xa000
	global_load_lds_dwordx4 v[4:5], off
	v_lshl_add_u64 v[0:1], v[0:1], 0, s[14:15]
	s_mov_b32 m0, s60
	s_add_u32 s18, s44, 0x10080
	global_load_lds_dwordx4 v[0:1], off
	v_lshl_add_u64 v[0:1], v[2:3], 0, s[14:15]
	s_mov_b32 m0, s61
	s_addc_u32 s19, s45, 0
	global_load_lds_dwordx4 v[0:1], off
	s_add_i32 m0, s56, 0x1c000
	v_lshl_add_u64 v[0:1], s[18:19], 0, v[132:133]
	global_load_lds_dwordx4 v[0:1], off
	v_lshl_add_u64 v[0:1], s[18:19], 0, v[128:129]
	s_add_i32 m0, s56, 0x1e000
	s_cmpk_lt_u32 s3, 0x100
	global_load_lds_dwordx4 v[0:1], off
	s_waitcnt vmcnt(8)
	s_barrier
	v_lshrrev_b32_e32 v1, 1, v8
	v_and_b32_e32 v1, 24, v1
	v_and_b32_e32 v0, 15, v8
	v_lshlrev_b32_e32 v2, 1, v1
	v_lshl_or_b32 v148, s16, 6, v0
	v_lshl_or_b32 v0, v0, 6, v2
	v_lshlrev_b32_e32 v2, 2, v8
	v_and_b32_e32 v2, 32, v2
	v_bitop3_b32 v3, v0, s17, v2 bitop3:0xde
	s_waitcnt vmcnt(6)
	s_cselect_b64 s[16:17], -1, 0
	s_add_u32 s18, s33, s89
	v_bitop3_b32 v149, v0, s21, v2 bitop3:0xde
	v_or_b32_e32 v0, s20, v1
	s_addc_u32 s19, s30, s50
	s_add_i32 s62, 0, 0x10000
	s_add_i32 s63, 0, 0x14000
	s_sext_i32_i8 s5, s2
	v_mov_b64_e32 v[138:139], 0x400
	v_mov_b64_e32 v[140:141], 0x3ff
	v_add_u32_e32 v150, s62, v149
	v_add_u32_e32 v151, s63, v149
	v_add_u32_e32 v152, 0, v3
	s_mov_b64 s[20:21], 0x100
	s_mov_b64 s[22:23], 0x180
	v_mov_b32_e32 v153, 0x358637bd
	s_mov_b32 s64, 0xf800000
	v_mov_b32_e32 v154, 0x260
	v_lshlrev_b32_e32 v136, 1, v0
	s_mov_b64 s[24:25], 0x80000
	s_mov_b64 s[26:27], 0x90000
	s_mov_b64 s[28:29], 0xa0000
	s_mov_b64 s[30:31], 0xb0000
	s_barrier
	s_branch .LBB0_490

; #define PG8_STAGE(bufoff, gbase, voff) do { _Pragma("unroll") for (int _i = 0; _i < 2; ++_i) \
;         __builtin_amdgcn_global_load_lds((const unsigned*)((const char*)(gbase) + (voff)[_i]), (PG8_LAS unsigned*)(lds + (bufoff) + ldsw + _i * 8192), 16, 0, 0); } while (0)
; #define PG8_WAIT_V(n) asm volatile("s_waitcnt vmcnt(" #n ")" ::: "memory")
; #define PG8_BAR __builtin_amdgcn_s_barrier()
; template <class Epi, class Sched, bool ALIGN_EPI = false, bool SP2 = false>
; __device__ __forceinline__ void gemm_phase(PG8_LAS unsigned char* lds, const Gemm g, const Sched& S, const Epi& E, int wv) {
;     ...
;     const unsigned ldsw = (unsigned)wid * 1024u;
;     const int aoff = lds_byte(wr * 64 + fr, fq * 8), boff = lds_byte(wc * 32 + fr, fq * 8);
;     ...
;         PG8_STAGE(PG8_SB(0, 0), cB, voffB); PG8_STAGE(PG8_SB(0, 1), cB + hstepB, voffB); PG8_STAGE(PG8_SA(0, 0), cA, voffA); PG8_STAGE(PG8_SA(0, 1), cA + hstepA, voffA);
;         if (wr == 1) PG8_BAR;
;         PG8_WAIT_V(2); PG8_BAR;
;         PG8_STAGE(PG8_SB(1, 0), cB + kstep, voffB); PG8_STAGE(PG8_SA(1, 0), cA + kstep, voffA); PG8_STAGE(PG8_SB(1, 1), cB + hstepB + kstep, voffB);
;         PG8_WAIT_V(6); PG8_BAR;
.LBB0_668:
	s_add_u32 s10, s78, 0xd300000
	s_addc_u32 s11, s79, 0
	s_lshl_b32 s12, s12, 5
	s_and_b32 s18, s12, 0x60
	s_mov_b64 s[12:13], 0x80
	s_add_i32 m0, s31, 0x18000
	v_lshl_add_u64 v[6:7], v[6:7], 0, s[12:13]
	s_lshl_b32 s15, s3, 13
	s_lshl_b32 s19, s18, 7
	global_load_lds_dwordx4 v[6:7], off
	v_lshl_add_u64 v[2:3], v[2:3], 0, s[12:13]
	s_add_i32 m0, s31, 0x1a000
	s_add_i32 s50, s31, 0x8000
	s_add_i32 s51, s31, 0xa000
	global_load_lds_dwordx4 v[2:3], off
	v_lshl_add_u64 v[0:1], v[0:1], 0, s[12:13]
	s_mov_b32 m0, s50
	s_add_u32 s16, s36, 0x80080
	global_load_lds_dwordx4 v[0:1], off
	v_lshl_add_u64 v[0:1], v[4:5], 0, s[12:13]
	s_mov_b32 m0, s51
	s_addc_u32 s17, s37, 0
	global_load_lds_dwordx4 v[0:1], off
	s_add_i32 m0, s31, 0x1c000
	v_lshl_add_u64 v[0:1], s[16:17], 0, v[134:135]
	global_load_lds_dwordx4 v[0:1], off
	v_lshl_add_u64 v[0:1], s[16:17], 0, v[138:139]
	s_add_i32 m0, s31, 0x1e000
	s_cmpk_lt_u32 s14, 0x100
	global_load_lds_dwordx4 v[0:1], off
	s_waitcnt vmcnt(8)
	s_barrier
	v_lshrrev_b32_e32 v1, 1, v8
	v_and_b32_e32 v1, 24, v1
	v_and_b32_e32 v0, 15, v8
	v_lshlrev_b32_e32 v2, 1, v1
	v_lshl_or_b32 v152, s3, 6, v0
	v_lshl_or_b32 v0, v0, 6, v2
	v_lshlrev_b32_e32 v2, 2, v8
	v_and_b32_e32 v2, 32, v2
	v_bitop3_b32 v3, v0, s15, v2 bitop3:0xde
	v_bitop3_b32 v153, v0, s19, v2 bitop3:0xde
	v_lshlrev_b32_e32 v0, 15, v9
	v_and_b32_e32 v0, 0xffff0000, v0
	v_or_b32_e32 v154, s18, v1
	v_lshl_add_u32 v0, v10, 12, v0
	v_and_b32_e32 v1, 1, v9
	v_lshl_or_b32 v0, v1, 6, v0
	v_lshl_add_u32 v140, v11, 1, v0
	v_lshlrev_b32_e32 v0, 15, v12
	v_and_b32_e32 v0, 0xffff0000, v0
	s_waitcnt vmcnt(6)
	v_lshl_add_u32 v0, v13, 12, v0
	v_and_b32_e32 v1, 1, v12
	s_cselect_b64 s[14:15], -1, 0
	v_lshl_or_b32 v0, v1, 6, v0
	s_add_i32 s53, 0, 0x10000
	s_add_i32 s54, 0, 0x14000
	s_sext_i32_i8 s59, s2
	s_ashr_i32 s52, s89, 31
	v_mov_b32_e32 v141, v135
	v_lshl_add_u32 v142, v14, 1, v0
	v_mov_b32_e32 v143, v135
	v_mov_b64_e32 v[144:145], 0x200
	v_mov_b64_e32 v[146:147], 0x1ff
	v_add_u32_e32 v155, s53, v153
	v_add_u32_e32 v156, s54, v153
	v_add_u32_e32 v157, 0, v3
	s_mov_b32 s55, 0x80000
	s_mov_b64 s[16:17], 0x90000
	s_mov_b32 s56, 0x90000
	s_mov_b64 s[18:19], 0xa0000
	s_mov_b32 s57, 0xa0000
	s_mov_b64 s[20:21], 0xb0000
	s_mov_b32 s58, 0xb0000
	s_barrier
	s_branch .LBB0_671

; #define PG8_STAGE(bufoff, gbase, voff) do { _Pragma("unroll") for (int _i = 0; _i < 2; ++_i) \
;         __builtin_amdgcn_global_load_lds((const unsigned*)((const char*)(gbase) + (voff)[_i]), (PG8_LAS unsigned*)(lds + (bufoff) + ldsw + _i * 8192), 16, 0, 0); } while (0)
; #define PG8_WAIT_V(n) asm volatile("s_waitcnt vmcnt(" #n ")" ::: "memory")
; #define PG8_BAR __builtin_amdgcn_s_barrier()
; template <class Epi, class Sched, bool ALIGN_EPI = false, bool SP2 = false>
; __device__ __forceinline__ void gemm_phase(PG8_LAS unsigned char* lds, const Gemm g, const Sched& S, const Epi& E, int wv) {
;     ...
;     const unsigned ldsw = (unsigned)wid * 1024u;
;     const int aoff = lds_byte(wr * 64 + fr, fq * 8), boff = lds_byte(wc * 32 + fr, fq * 8);
;     ...
;         PG8_STAGE(PG8_SB(0, 0), cB, voffB); PG8_STAGE(PG8_SB(0, 1), cB + hstepB, voffB); PG8_STAGE(PG8_SA(0, 0), cA, voffA); PG8_STAGE(PG8_SA(0, 1), cA + hstepA, voffA);
;         if (wr == 1) PG8_BAR;
;         PG8_WAIT_V(2); PG8_BAR;
;         PG8_STAGE(PG8_SB(1, 0), cB + kstep, voffB); PG8_STAGE(PG8_SA(1, 0), cA + kstep, voffA); PG8_STAGE(PG8_SB(1, 1), cB + hstepB + kstep, voffB);
;         PG8_WAIT_V(6); PG8_BAR;
.LBB0_747:
	s_add_u32 s10, s78, 0xd300000
	s_addc_u32 s11, s79, 0
	s_add_u32 s12, s78, 0x11300000
	s_addc_u32 s13, s79, 0
	s_lshl_b32 s14, s14, 5
	s_and_b32 s20, s14, 0x60
	s_mov_b64 s[14:15], 0x80
	s_add_i32 m0, s35, 0x18000
	v_lshl_add_u64 v[6:7], v[6:7], 0, s[14:15]
	s_lshl_b32 s17, s3, 13
	s_lshl_b32 s21, s20, 7
	global_load_lds_dwordx4 v[6:7], off
	v_lshl_add_u64 v[2:3], v[2:3], 0, s[14:15]
	s_add_i32 m0, s35, 0x1a000
	s_add_i32 s52, s35, 0x8000
	s_add_i32 s53, s35, 0xa000
	global_load_lds_dwordx4 v[2:3], off
	v_lshl_add_u64 v[0:1], v[0:1], 0, s[14:15]
	s_mov_b32 m0, s52
	s_add_u32 s18, s38, 0x80080
	global_load_lds_dwordx4 v[0:1], off
	v_lshl_add_u64 v[0:1], v[4:5], 0, s[14:15]
	s_mov_b32 m0, s53
	s_addc_u32 s19, s39, 0
	global_load_lds_dwordx4 v[0:1], off
	s_add_i32 m0, s35, 0x1c000
	v_lshl_add_u64 v[0:1], s[18:19], 0, v[130:131]
	global_load_lds_dwordx4 v[0:1], off
	v_lshl_add_u64 v[0:1], s[18:19], 0, v[134:135]
	s_add_i32 m0, s35, 0x1e000
	s_cmpk_lt_u32 s16, 0x100
	global_load_lds_dwordx4 v[0:1], off
	s_waitcnt vmcnt(8)
	s_barrier
	v_lshrrev_b32_e32 v1, 1, v8
	v_and_b32_e32 v1, 24, v1
	v_and_b32_e32 v0, 15, v8
	v_lshlrev_b32_e32 v2, 1, v1
	v_lshl_or_b32 v150, s3, 6, v0
	v_lshl_or_b32 v0, v0, 6, v2
	v_lshlrev_b32_e32 v2, 2, v8
	v_and_b32_e32 v2, 32, v2
	v_bitop3_b32 v3, v0, s17, v2 bitop3:0xde
	v_bitop3_b32 v151, v0, s21, v2 bitop3:0xde
	v_lshlrev_b32_e32 v0, 15, v9
	v_and_b32_e32 v0, 0xffff0000, v0
	v_or_b32_e32 v152, s20, v1
	v_lshl_add_u32 v0, v10, 12, v0
	v_and_b32_e32 v1, 1, v9
	v_lshl_or_b32 v0, v1, 6, v0
	v_lshl_add_u32 v136, v11, 1, v0
	v_lshlrev_b32_e32 v0, 15, v12
	v_and_b32_e32 v0, 0xffff0000, v0
	s_waitcnt vmcnt(6)
	v_lshl_add_u32 v0, v13, 12, v0
	v_and_b32_e32 v1, 1, v12
	s_cselect_b64 s[16:17], -1, 0
	v_lshl_or_b32 v0, v1, 6, v0
	s_add_i32 s55, 0, 0x10000
	s_add_i32 s56, 0, 0x14000
	s_sext_i32_i8 s57, s2
	s_ashr_i32 s54, s89, 31
	v_mov_b32_e32 v137, v131
	v_lshl_add_u32 v138, v14, 1, v0
	v_mov_b32_e32 v139, v131
	v_mov_b64_e32 v[140:141], 0x200
	v_mov_b64_e32 v[142:143], 0x1ff
	v_add_u32_e32 v153, s55, v151
	v_add_u32_e32 v154, s56, v151
	v_add_u32_e32 v155, 0, v3
	s_mov_b64 s[18:19], 0x90000
	s_mov_b64 s[20:21], 0xa0000
	s_mov_b64 s[22:23], 0xb0000
	s_barrier
	s_branch .LBB0_750

; #define PG8_STAGE(bufoff, gbase, voff) do { _Pragma("unroll") for (int _i = 0; _i < 2; ++_i) \
;         __builtin_amdgcn_global_load_lds((const unsigned*)((const char*)(gbase) + (voff)[_i]), (PG8_LAS unsigned*)(lds + (bufoff) + ldsw + _i * 8192), 16, 0, 0); } while (0)
; #define PG8_WAIT_V(n) asm volatile("s_waitcnt vmcnt(" #n ")" ::: "memory")
; #define PG8_BAR __builtin_amdgcn_s_barrier()
; template <class Epi, class Sched, bool ALIGN_EPI = false, bool SP2 = false>
; __device__ __forceinline__ void gemm_phase(PG8_LAS unsigned char* lds, const Gemm g, const Sched& S, const Epi& E, int wv) {
;     ...
;     const unsigned ldsw = (unsigned)wid * 1024u;
;     const int aoff = lds_byte(wr * 64 + fr, fq * 8), boff = lds_byte(wc * 32 + fr, fq * 8);
;     ...
;         PG8_STAGE(PG8_SB(0, 0), cB, voffB); PG8_STAGE(PG8_SB(0, 1), cB + hstepB, voffB); PG8_STAGE(PG8_SA(0, 0), cA, voffA); PG8_STAGE(PG8_SA(0, 1), cA + hstepA, voffA);
;         if (wr == 1) PG8_BAR;
;         PG8_WAIT_V(2); PG8_BAR;
;         PG8_STAGE(PG8_SB(1, 0), cB + kstep, voffB); PG8_STAGE(PG8_SA(1, 0), cA + kstep, voffA); PG8_STAGE(PG8_SB(1, 1), cB + hstepB + kstep, voffB);
;         PG8_WAIT_V(6); PG8_BAR;
.LBB0_822:
	s_lshl_b32 s8, s8, 5
	s_and_b32 s14, s8, 0x60
	s_mov_b64 s[8:9], 0x80
	s_add_i32 m0, s31, 0x18000
	v_lshl_add_u64 v[6:7], v[6:7], 0, s[8:9]
	s_ashr_i32 s50, s89, 31
	s_lshl_b32 s13, s12, 13
	s_lshl_b32 s15, s14, 7
	global_load_lds_dwordx4 v[6:7], off
	v_lshl_add_u64 v[4:5], v[4:5], 0, s[8:9]
	s_add_i32 m0, s31, 0x1a000
	s_add_i32 s51, s31, 0x8000
	s_add_i32 s52, s31, 0xa000
	global_load_lds_dwordx4 v[4:5], off
	v_lshl_add_u64 v[0:1], v[0:1], 0, s[8:9]
	s_mov_b32 m0, s51
	s_add_u32 s10, s34, 0x80080
	global_load_lds_dwordx4 v[0:1], off
	v_lshl_add_u64 v[0:1], v[2:3], 0, s[8:9]
	s_mov_b32 m0, s52
	s_addc_u32 s11, s35, 0
	global_load_lds_dwordx4 v[0:1], off
	s_add_i32 m0, s31, 0x1c000
	v_lshl_add_u64 v[0:1], s[10:11], 0, v[132:133]
	global_load_lds_dwordx4 v[0:1], off
	v_lshl_add_u64 v[0:1], s[10:11], 0, v[128:129]
	s_add_i32 m0, s31, 0x1e000
	s_load_dwordx2 s[10:11], s[0:1], 0xc8
	global_load_lds_dwordx4 v[0:1], off
	s_waitcnt vmcnt(8)
	s_barrier
	v_lshrrev_b32_e32 v1, 1, v8
	v_and_b32_e32 v1, 24, v1
	v_and_b32_e32 v0, 15, v8
	v_lshlrev_b32_e32 v2, 1, v1
	v_lshl_or_b32 v146, s12, 6, v0
	v_lshl_or_b32 v0, v0, 6, v2
	v_lshlrev_b32_e32 v2, 2, v8
	v_and_b32_e32 v2, 32, v2
	v_bitop3_b32 v3, v0, s13, v2 bitop3:0xde
	v_bitop3_b32 v147, v0, s15, v2 bitop3:0xde
	v_lshlrev_b32_e32 v0, 15, v12
	v_and_b32_e32 v0, 0xffff0000, v0
	v_or_b32_e32 v148, s14, v1
	v_lshl_add_u32 v0, v13, 12, v0
	v_and_b32_e32 v1, 1, v12
	v_lshl_or_b32 v0, v1, 6, v0
	v_lshl_add_u32 v136, v14, 1, v0
	v_lshlrev_b32_e32 v0, 15, v9
	v_and_b32_e32 v0, 0xffff0000, v0
	s_waitcnt vmcnt(6)
	s_cmpk_lt_u32 s3, 0x100
	v_lshl_add_u32 v0, v10, 12, v0
	v_and_b32_e32 v1, 1, v9
	s_cselect_b64 s[12:13], -1, 0
	v_lshl_or_b32 v0, v1, 6, v0
	s_add_i32 s53, 0, 0x10000
	s_add_i32 s54, 0, 0x14000
	s_sext_i32_i8 s59, s2
	v_mov_b32_e32 v137, v133
	v_lshl_add_u32 v138, v11, 1, v0
	v_mov_b32_e32 v139, v133
	v_mov_b64_e32 v[140:141], 0x200
	v_mov_b64_e32 v[142:143], 0x1ff
	v_add_u32_e32 v149, s53, v147
	v_add_u32_e32 v150, s54, v147
	v_add_u32_e32 v151, 0, v3
	s_mov_b64 s[14:15], 0x100000
	s_mov_b32 s55, 0x100000
	s_mov_b64 s[16:17], 0x120000
	s_mov_b32 s56, 0x120000
	s_mov_b64 s[18:19], 0x140000
	s_mov_b32 s57, 0x140000
	s_mov_b64 s[20:21], 0x160000
	s_mov_b32 s58, 0x160000
	s_barrier
	s_branch .LBB0_825

; #define PG8_STAGE(bufoff, gbase, voff) do { _Pragma("unroll") for (int _i = 0; _i < 2; ++_i) \
;         __builtin_amdgcn_global_load_lds((const unsigned*)((const char*)(gbase) + (voff)[_i]), (PG8_LAS unsigned*)(lds + (bufoff) + ldsw + _i * 8192), 16, 0, 0); } while (0)
; #define PG8_WAIT_V(n) asm volatile("s_waitcnt vmcnt(" #n ")" ::: "memory")
; #define PG8_BAR __builtin_amdgcn_s_barrier()
; template <class Epi, class Sched, bool ALIGN_EPI = false, bool SP2 = false>
; __device__ __forceinline__ void gemm_phase(PG8_LAS unsigned char* lds, const Gemm g, const Sched& S, const Epi& E, int wv) {
;     ...
;     const unsigned ldsw = (unsigned)wid * 1024u;
;     const int aoff = lds_byte(wr * 64 + fr, fq * 8), boff = lds_byte(wc * 32 + fr, fq * 8);
;     ...
;         PG8_STAGE(PG8_SB(0, 0), cB, voffB); PG8_STAGE(PG8_SB(0, 1), cB + hstepB, voffB); PG8_STAGE(PG8_SA(0, 0), cA, voffA); PG8_STAGE(PG8_SA(0, 1), cA + hstepA, voffA);
;         if (wr == 1) PG8_BAR;
;         PG8_WAIT_V(2); PG8_BAR;
;         PG8_STAGE(PG8_SB(1, 0), cB + kstep, voffB); PG8_STAGE(PG8_SA(1, 0), cA + kstep, voffA); PG8_STAGE(PG8_SB(1, 1), cB + hstepB + kstep, voffB);
;         PG8_WAIT_V(6); PG8_BAR;
.LBB0_959:
	s_add_u32 s12, s78, 0x9300000
	s_addc_u32 s13, s79, 0
	s_add_u32 s14, s78, 0x1f300000
	s_addc_u32 s15, s79, 0
	s_add_u32 s4, s34, 0x80080
	s_mov_b64 s[16:17], 0x80
	s_addc_u32 s5, s35, 0
	s_add_i32 m0, s45, 0x18000
	v_lshl_add_u64 v[6:7], v[6:7], 0, s[16:17]
	global_load_lds_dwordx4 v[6:7], off
	v_lshl_add_u64 v[4:5], v[4:5], 0, s[16:17]
	s_add_i32 m0, s45, 0x1a000
	s_add_i32 s49, s45, 0x8000
	global_load_lds_dwordx4 v[4:5], off
	v_lshl_add_u64 v[0:1], v[0:1], 0, s[16:17]
	s_mov_b32 m0, s49
	s_add_i32 s50, s45, 0xa000
	global_load_lds_dwordx4 v[0:1], off
	v_lshl_add_u64 v[0:1], v[2:3], 0, s[16:17]
	s_mov_b32 m0, s50
	v_and_b32_e32 v150, 15, v8
	global_load_lds_dwordx4 v[0:1], off
	s_add_i32 m0, s45, 0x1c000
	v_lshl_add_u64 v[0:1], s[4:5], 0, v[132:133]
	global_load_lds_dwordx4 v[0:1], off
	v_lshl_add_u64 v[0:1], s[4:5], 0, v[128:129]
	s_add_i32 m0, s45, 0x1e000
	v_lshlrev_b32_e32 v2, 2, v8
	global_load_lds_dwordx4 v[0:1], off
	s_waitcnt vmcnt(8)
	s_barrier
	v_lshrrev_b32_e32 v0, 1, v8
	v_and_b32_e32 v0, 24, v0
	v_lshlrev_b32_e32 v1, 1, v0
	s_sext_i32_i16 s29, s2
	v_lshl_or_b32 v1, v150, 6, v1
	s_lshl_b32 s2, s18, 13
	v_and_b32_e32 v2, 32, v2
	v_bitop3_b32 v3, v1, s2, v2 bitop3:0xde
	s_lshl_b32 s2, s8, 5
	s_and_b32 s4, s2, 0x60
	s_lshl_b32 s2, s4, 7
	v_bitop3_b32 v151, v1, s2, v2 bitop3:0xde
	v_lshlrev_b32_e32 v1, 15, v13
	v_and_b32_e32 v1, 0xffff0000, v1
	v_lshl_add_u32 v1, v12, 12, v1
	v_and_b32_e32 v2, 1, v13
	v_lshl_or_b32 v1, v2, 6, v1
	v_lshl_add_u32 v140, v14, 1, v1
	v_lshlrev_b32_e32 v1, 15, v9
	s_ashr_i32 s51, s89, 31
	s_lshl_b32 s52, s18, 6
	v_and_b32_e32 v1, 0xffff0000, v1
	s_waitcnt vmcnt(6)
	s_cmpk_lt_u32 s3, 0x100
	v_lshl_add_u32 v1, v10, 12, v1
	v_and_b32_e32 v2, 1, v9
	s_cselect_b64 s[18:19], -1, 0
	v_lshl_or_b32 v1, v2, 6, v1
	s_add_i32 s53, 0, 0x10000
	s_add_i32 s54, 0, 0x14000
	v_cmp_lt_u32_e64 s[2:3], 13, v150
	v_add_u32_e32 v138, -14, v150
	v_mov_b32_e32 v139, v137
	v_or_b32_e32 v152, s4, v0
	v_mov_b32_e32 v141, v137
	v_lshl_add_u32 v142, v11, 1, v1
	v_mov_b32_e32 v143, v137
	v_mov_b64_e32 v[144:145], 0xb00
	v_mov_b64_e32 v[146:147], 0xaff
	v_add_u32_e32 v153, s53, v151
	v_add_u32_e32 v154, s54, v151
	v_add_u32_e32 v155, 0, v3
	s_movk_i32 s55, 0x5800
	s_movk_i32 s56, 0x2c00
	s_lshl_b32 s8, s4, 1
	v_lshlrev_b32_e32 v136, 1, v0
	s_mov_b32 s57, 0xb000000
	s_mov_b32 s58, s9
	s_barrier
	s_branch .LBB0_962

; #define PG8_STAGE(bufoff, gbase, voff) do { _Pragma("unroll") for (int _i = 0; _i < 2; ++_i) \
;         __builtin_amdgcn_global_load_lds((const unsigned*)((const char*)(gbase) + (voff)[_i]), (PG8_LAS unsigned*)(lds + (bufoff) + ldsw + _i * 8192), 16, 0, 0); } while (0)
; #define PG8_WAIT_V(n) asm volatile("s_waitcnt vmcnt(" #n ")" ::: "memory")
; #define PG8_BAR __builtin_amdgcn_s_barrier()
; template <class Epi, class Sched, bool ALIGN_EPI = false, bool SP2 = false>
; __device__ __forceinline__ void gemm_phase(PG8_LAS unsigned char* lds, const Gemm g, const Sched& S, const Epi& E, int wv) {
;     ...
;     const unsigned ldsw = (unsigned)wid * 1024u;
;     const int aoff = lds_byte(wr * 64 + fr, fq * 8), boff = lds_byte(wc * 32 + fr, fq * 8);
;     ...
;         PG8_STAGE(PG8_SB(0, 0), cB, voffB); PG8_STAGE(PG8_SB(0, 1), cB + hstepB, voffB); PG8_STAGE(PG8_SA(0, 0), cA, voffA); PG8_STAGE(PG8_SA(0, 1), cA + hstepA, voffA);
;         if (wr == 1) PG8_BAR;
;         PG8_WAIT_V(2); PG8_BAR;
;         PG8_STAGE(PG8_SB(1, 0), cB + kstep, voffB); PG8_STAGE(PG8_SA(1, 0), cA + kstep, voffA); PG8_STAGE(PG8_SB(1, 1), cB + hstepB + kstep, voffB);
;         PG8_WAIT_V(6); PG8_BAR;
.LBB0_1101:
	s_add_u32 s10, s78, 0x5300000
	s_addc_u32 s11, s79, 0
	s_lshl_b32 s12, s12, 5
	s_and_b32 s20, s12, 0x60
	s_mov_b64 s[12:13], 0x80
	s_add_i32 m0, s42, 0x18000
	v_lshl_add_u64 v[6:7], v[6:7], 0, s[12:13]
	s_ashr_i32 s47, s89, 31
	s_lshl_b32 s17, s4, 13
	s_lshl_b32 s18, s20, 7
	global_load_lds_dwordx4 v[6:7], off
	v_lshl_add_u64 v[2:3], v[2:3], 0, s[12:13]
	s_add_i32 m0, s42, 0x1a000
	s_add_i32 s48, s42, 0x8000
	s_add_i32 s49, s42, 0xa000
	global_load_lds_dwordx4 v[2:3], off
	v_lshl_add_u64 v[0:1], v[0:1], 0, s[12:13]
	s_mov_b32 m0, s48
	s_add_u32 s14, s28, 0x160080
	global_load_lds_dwordx4 v[0:1], off
	v_lshl_add_u64 v[0:1], v[4:5], 0, s[12:13]
	s_mov_b32 m0, s49
	s_addc_u32 s15, s29, 0
	global_load_lds_dwordx4 v[0:1], off
	s_add_i32 m0, s42, 0x1c000
	v_lshl_add_u64 v[0:1], s[14:15], 0, v[132:133]
	global_load_lds_dwordx4 v[0:1], off
	v_lshl_add_u64 v[0:1], s[14:15], 0, v[128:129]
	s_add_i32 m0, s42, 0x1e000
	s_sext_i32_i8 s59, s2
	global_load_lds_dwordx4 v[0:1], off
	s_waitcnt vmcnt(8)
	s_barrier
	v_lshrrev_b32_e32 v1, 1, v8
	v_and_b32_e32 v1, 24, v1
	v_and_b32_e32 v0, 15, v8
	v_lshlrev_b32_e32 v2, 1, v1
	v_lshl_or_b32 v146, s4, 6, v0
	v_lshl_or_b32 v0, v0, 6, v2
	v_lshlrev_b32_e32 v2, 2, v8
	v_and_b32_e32 v2, 32, v2
	v_bitop3_b32 v3, v0, s17, v2 bitop3:0xde
	v_bitop3_b32 v147, v0, s18, v2 bitop3:0xde
	v_or_b32_e32 v148, s20, v1
	v_lshrrev_b32_e32 v1, 1, v14
	v_mul_lo_u32 v0, v13, s5
	s_cmpk_lt_u32 s3, 0x100
	v_mad_u64_u32 v[0:1], s[2:3], v1, s16, v[0:1]
	v_or_b32_e32 v0, v0, v15
	s_mov_b64 s[18:19], 0x160080
	v_add_lshl_u32 v0, v0, v16, 1
	v_mov_b32_e32 v1, v133
	v_lshl_add_u64 v[136:137], v[0:1], 0, s[18:19]
	v_lshrrev_b32_e32 v1, 1, v9
	v_mul_lo_u32 v0, v10, s5
	v_mad_u64_u32 v[0:1], s[2:3], v1, s16, v[0:1]
	s_waitcnt vmcnt(6)
	v_or_b32_e32 v0, v0, v11
	s_cselect_b64 s[14:15], -1, 0
	v_add_lshl_u32 v0, v0, v12, 1
	v_mov_b32_e32 v1, v133
	s_add_i32 s50, 0, 0x10000
	s_add_i32 s51, 0, 0x14000
	v_lshl_add_u64 v[138:139], v[0:1], 0, s[18:19]
	v_mov_b64_e32 v[140:141], 0x200
	v_mov_b64_e32 v[142:143], 0x1ff
	v_add_u32_e32 v149, s50, v147
	v_add_u32_e32 v150, s51, v147
	v_add_u32_e32 v151, 0, v3
	s_mov_b64 s[16:17], 0x80000
	s_mov_b32 s52, 0x80000
	s_mov_b64 s[18:19], 0x90000
	s_mov_b32 s53, 0x90000
	s_mov_b64 s[20:21], 0xa0000
	s_mov_b32 s54, 0xa0000
	s_mov_b64 s[22:23], 0xb0000
	s_mov_b32 s55, 0xb0000
	s_barrier
	s_branch .LBB0_1104
